# retention V tile odd-row shift (bank conflicts), FFN-up epilogue canonicalising max removed, first seam on XCD barrier
# baseline (speedup 1.0000x reference)
;   __device__ __forceinline__ void operator()(const f32x4 (&acc)[2][2][4][2], const pg8::Unit& u, int wr, int wc, int fr, int fq) const {
;     ...
; #pragma unroll
;       for (int m = 0; m < 4; ++m) {
;         const int lrow = ai * 128 + wr * 64 + m * 16 + fr;
;         const int row = u.pm * 256 + lrow;
;         const int tok = (seg - 1) * 256 + lrow;
;         bf16_t* rowp = O + (size_t)row * ldc + col_off;
; #pragma unroll
;         for (int bj = 0; bj < 2; ++bj) {
;           const int c = colt + bj * 128;
;           f32x4 v0 = acc[ai][bj][m][0], v1 = acc[ai][bj][m][1];
;           if (mode == 5) {
;             float* pp = (float*)O + ((size_t)(u.kp * 2048 + (u.pm / 33) * 256 + lrow) * 1024 + c);
;             *(f32x4*)pp = v0; *(f32x4*)(pp + 4) = v1;
;             continue;
;           }
;           if (mode == 1) {
; #pragma unroll
;             for (int i = 0; i < 4; ++i) { float a = fmaxf(v0[i], 0.f), b = fmaxf(v1[i], 0.f); v0[i] = a * a; v1[i] = b * b; }
;           } else if (mode == 2) {
;             const int hc = c % 96;
;             if (islat && hc >= 64) {
;               const int j = hc - 64, part = j >> 4, g = (j & 15) >> 3, pos = part ? (tok & 63) : (tok >> 6);
;               const f32x4 cs4 = *(const f32x4*)(tab + pos * 8 + 4 * g), sn4 = *(const f32x4*)(tab + 1024 + pos * 8 + 4 * g);
;               const f32x4 o0 = v0 * cs4 - v1 * sn4, o1 = v0 * sn4 + v1 * cs4; v0 = o0; v1 = o1;
;             }
;             v0 = v0 * scale; v1 = v1 * scale;
;           } else if (mode == 3) {
;             if (u.pn < 8) {
;               if (islat) {
;                 const f32x4 cs4 = rpart ? tcm[m] : tca[ai], sn4 = rpart ? tsm[m] : tsa[ai];
;                 const f32x4 o0 = v0 * cs4 - v1 * sn4, o1 = v0 * sn4 + v1 * cs4; v0 = o0; v1 = o1;
;               }
;               if (u.pn >= 4) { v0 = v0 * scale; v1 = v1 * scale; }
;             }
;           } else if (mode == 4) {
;             const u32x4 old = oldv[ai][m][bj];
;             const float ov[8] = {bflo(old.x), bfhi(old.x), bflo(old.y), bfhi(old.y), bflo(old.z), bfhi(old.z), bflo(old.w), bfhi(old.w)};
; #pragma unroll
;             for (int i = 0; i < 4; ++i) { const float a = v0[i], b = v1[i]; v0[i] = a / (1.f + __expf(-a)) * ov[i]; v1[i] = b / (1.f + __expf(-b)) * ov[4 + i]; }
;           } else if (cs) {
.LBB0_173:
	v_mov_b32_e32 v140, v142
	s_lshl_b32 s15, s47, 8
	v_lshrrev_b32_e32 v141, 1, v140
	v_and_or_b32 v140, v140, 15, s42
	v_and_or_b32 v141, v141, 24, s15
	v_lshl_add_u32 v140, s22, 8, v140
	v_or_b32_e32 v146, s43, v141
	v_ashrrev_i32_e32 v141, 31, v140
	v_max_f32_e32 v126, 0, v126
	v_max_f32_e32 v122, 0, v122
	v_max_f32_e32 v127, 0, v127
	v_max_f32_e32 v123, 0, v123
	v_lshlrev_b64 v[148:149], 13, v[140:141]
	v_pk_mul_f32 v[126:127], v[126:127], v[126:127]
	v_pk_mul_f32 v[122:123], v[122:123], v[122:123]
	v_max_f32_e32 v128, 0, v128
	v_max_f32_e32 v124, 0, v124
	v_max_f32_e32 v129, 0, v129
	v_max_f32_e32 v125, 0, v125
	v_ashrrev_i32_e32 v147, 31, v146
	v_lshl_add_u64 v[148:149], s[84:85], 0, v[148:149]
	v_pk_mul_f32 v[128:129], v[128:129], v[128:129]
	v_pk_mul_f32 v[150:151], v[124:125], v[124:125]
	v_cvt_pk_bf16_f32 v124, v126, v127
	v_cvt_pk_bf16_f32 v126, v122, v123
	v_lshlrev_b64 v[122:123], 1, v[146:147]
	v_cvt_pk_bf16_f32 v125, v128, v129
	v_cvt_pk_bf16_f32 v127, v150, v151
	v_lshl_add_u64 v[128:129], v[148:149], 0, v[122:123]
	v_max_f32_e32 v114, 0, v114
	v_max_f32_e32 v115, 0, v115
	global_store_dwordx4 v[128:129], v[124:127], off
	s_nop 1
	v_pk_mul_f32 v[124:125], v[114:115], v[114:115]
	v_max_f32_e32 v116, 0, v116
	v_max_f32_e32 v118, 0, v118
	v_max_f32_e32 v119, 0, v119
	v_max_f32_e32 v114, 0, v120
	v_max_f32_e32 v115, 0, v121
	v_max_f32_e32 v117, 0, v117
	v_pk_mul_f32 v[118:119], v[118:119], v[118:119]
	v_pk_mul_f32 v[120:121], v[114:115], v[114:115]
	v_pk_mul_f32 v[126:127], v[116:117], v[116:117]
	v_cvt_pk_bf16_f32 v114, v118, v119
	v_cvt_pk_bf16_f32 v115, v120, v121
	v_cvt_pk_bf16_f32 v116, v124, v125
	v_cvt_pk_bf16_f32 v117, v126, v127
	v_max_f32_e32 v106, 0, v106
	v_max_f32_e32 v107, 0, v107
	global_store_dwordx4 v[128:129], v[114:117], off offset:256
	s_nop 1
	v_or_b32_e32 v114, 16, v140
	v_pk_mul_f32 v[116:117], v[106:107], v[106:107]
	v_ashrrev_i32_e32 v115, 31, v114
	v_max_f32_e32 v108, 0, v108
	v_lshlrev_b64 v[114:115], 13, v[114:115]
	v_max_f32_e32 v110, 0, v110
	v_max_f32_e32 v111, 0, v111
	v_max_f32_e32 v106, 0, v112
	v_max_f32_e32 v107, 0, v113
	v_max_f32_e32 v109, 0, v109
	v_lshl_add_u64 v[114:115], s[84:85], 0, v[114:115]
	v_pk_mul_f32 v[110:111], v[110:111], v[110:111]
	v_pk_mul_f32 v[112:113], v[106:107], v[106:107]
	v_pk_mul_f32 v[118:119], v[108:109], v[108:109]
	v_cvt_pk_bf16_f32 v106, v110, v111
	v_cvt_pk_bf16_f32 v107, v112, v113
	v_cvt_pk_bf16_f32 v108, v116, v117
	v_cvt_pk_bf16_f32 v109, v118, v119
	v_lshl_add_u64 v[110:111], v[114:115], 0, v[122:123]
	v_max_f32_e32 v98, 0, v98
	v_max_f32_e32 v99, 0, v99
	global_store_dwordx4 v[110:111], v[106:109], off
	s_nop 1
	v_pk_mul_f32 v[106:107], v[98:99], v[98:99]
	v_max_f32_e32 v100, 0, v100
	v_max_f32_e32 v102, 0, v102
	v_max_f32_e32 v103, 0, v103
	v_max_f32_e32 v98, 0, v104
	v_max_f32_e32 v99, 0, v105
	v_max_f32_e32 v101, 0, v101
	v_pk_mul_f32 v[102:103], v[102:103], v[102:103]
	v_pk_mul_f32 v[104:105], v[98:99], v[98:99]
	v_pk_mul_f32 v[108:109], v[100:101], v[100:101]
	v_cvt_pk_bf16_f32 v98, v102, v103
	v_cvt_pk_bf16_f32 v99, v104, v105
	v_cvt_pk_bf16_f32 v100, v106, v107
	v_cvt_pk_bf16_f32 v101, v108, v109
	v_max_f32_e32 v90, 0, v90
	v_max_f32_e32 v91, 0, v91
	global_store_dwordx4 v[110:111], v[98:101], off offset:256
	s_nop 1
	v_or_b32_e32 v98, 32, v140
	v_pk_mul_f32 v[100:101], v[90:91], v[90:91]
	v_ashrrev_i32_e32 v99, 31, v98
	v_max_f32_e32 v92, 0, v92
	v_lshlrev_b64 v[98:99], 13, v[98:99]
	v_max_f32_e32 v94, 0, v94
	v_max_f32_e32 v95, 0, v95
	v_max_f32_e32 v90, 0, v96
	v_max_f32_e32 v91, 0, v97
	v_max_f32_e32 v93, 0, v93
	v_lshl_add_u64 v[98:99], s[84:85], 0, v[98:99]
	v_pk_mul_f32 v[94:95], v[94:95], v[94:95]
	v_pk_mul_f32 v[96:97], v[90:91], v[90:91]
	v_pk_mul_f32 v[102:103], v[92:93], v[92:93]
	v_cvt_pk_bf16_f32 v90, v94, v95
	v_cvt_pk_bf16_f32 v91, v96, v97
	v_cvt_pk_bf16_f32 v92, v100, v101
	v_cvt_pk_bf16_f32 v93, v102, v103
	v_lshl_add_u64 v[94:95], v[98:99], 0, v[122:123]
	v_max_f32_e32 v82, 0, v82
	v_max_f32_e32 v83, 0, v83
	global_store_dwordx4 v[94:95], v[90:93], off
	s_nop 1
	v_pk_mul_f32 v[90:91], v[82:83], v[82:83]
	v_max_f32_e32 v84, 0, v84
	v_max_f32_e32 v86, 0, v86
	v_max_f32_e32 v87, 0, v87
	v_max_f32_e32 v82, 0, v88
	v_max_f32_e32 v83, 0, v89
	v_max_f32_e32 v85, 0, v85
	v_pk_mul_f32 v[86:87], v[86:87], v[86:87]
	v_pk_mul_f32 v[88:89], v[82:83], v[82:83]
	v_pk_mul_f32 v[92:93], v[84:85], v[84:85]
	v_cvt_pk_bf16_f32 v82, v86, v87
	v_cvt_pk_bf16_f32 v83, v88, v89
	v_cvt_pk_bf16_f32 v84, v90, v91
	v_cvt_pk_bf16_f32 v85, v92, v93
	v_max_f32_e32 v74, 0, v74
	v_max_f32_e32 v75, 0, v75
	global_store_dwordx4 v[94:95], v[82:85], off offset:256
	s_nop 1
	v_or_b32_e32 v82, 48, v140
	v_pk_mul_f32 v[84:85], v[74:75], v[74:75]
	v_ashrrev_i32_e32 v83, 31, v82
	v_max_f32_e32 v76, 0, v76
	v_lshlrev_b64 v[82:83], 13, v[82:83]
	v_max_f32_e32 v78, 0, v78
	v_max_f32_e32 v79, 0, v79
	v_max_f32_e32 v74, 0, v80
	v_max_f32_e32 v75, 0, v81
	v_max_f32_e32 v77, 0, v77
	v_lshl_add_u64 v[82:83], s[84:85], 0, v[82:83]
	v_pk_mul_f32 v[78:79], v[78:79], v[78:79]
	v_pk_mul_f32 v[80:81], v[74:75], v[74:75]
	v_pk_mul_f32 v[86:87], v[76:77], v[76:77]
	v_cvt_pk_bf16_f32 v74, v78, v79
	v_cvt_pk_bf16_f32 v75, v80, v81
	v_cvt_pk_bf16_f32 v76, v84, v85
	v_cvt_pk_bf16_f32 v77, v86, v87
	v_lshl_add_u64 v[78:79], v[82:83], 0, v[122:123]
	v_max_f32_e32 v66, 0, v66
	v_max_f32_e32 v67, 0, v67
	global_store_dwordx4 v[78:79], v[74:77], off
	s_nop 1
	v_pk_mul_f32 v[74:75], v[66:67], v[66:67]
	v_max_f32_e32 v68, 0, v68
	v_max_f32_e32 v70, 0, v70
	v_max_f32_e32 v71, 0, v71
	v_max_f32_e32 v66, 0, v72
	v_max_f32_e32 v67, 0, v73
	v_max_f32_e32 v69, 0, v69
;   __device__ __forceinline__ void operator()(const f32x4 (&acc)[2][2][4][2], const pg8::Unit& u, int wr, int wc, int fr, int fq) const {
;     ...
;         for (int bj = 0; bj < 2; ++bj) {
;           const int c = colt + bj * 128;
;           f32x4 v0 = acc[ai][bj][m][0], v1 = acc[ai][bj][m][1];
;           if (mode == 5) {
;             float* pp = (float*)O + ((size_t)(u.kp * 2048 + (u.pm / 33) * 256 + lrow) * 1024 + c);
;             *(f32x4*)pp = v0; *(f32x4*)(pp + 4) = v1;
;             continue;
;           }
;           if (mode == 1) {
; #pragma unroll
;             for (int i = 0; i < 4; ++i) { float a = fmaxf(v0[i], 0.f), b = fmaxf(v1[i], 0.f); v0[i] = a * a; v1[i] = b * b; }
;           } else if (mode == 2) {
;             const int hc = c % 96;
;             if (islat && hc >= 64) {
;               const int j = hc - 64, part = j >> 4, g = (j & 15) >> 3, pos = part ? (tok & 63) : (tok >> 6);
;               const f32x4 cs4 = *(const f32x4*)(tab + pos * 8 + 4 * g), sn4 = *(const f32x4*)(tab + 1024 + pos * 8 + 4 * g);
;               const f32x4 o0 = v0 * cs4 - v1 * sn4, o1 = v0 * sn4 + v1 * cs4; v0 = o0; v1 = o1;
;             }
;             v0 = v0 * scale; v1 = v1 * scale;
;           } else if (mode == 3) {
;             if (u.pn < 8) {
;               if (islat) {
;                 const f32x4 cs4 = rpart ? tcm[m] : tca[ai], sn4 = rpart ? tsm[m] : tsa[ai];
;                 const f32x4 o0 = v0 * cs4 - v1 * sn4, o1 = v0 * sn4 + v1 * cs4; v0 = o0; v1 = o1;
;               }
;               if (u.pn >= 4) { v0 = v0 * scale; v1 = v1 * scale; }
;             }
;           } else if (mode == 4) {
;             const u32x4 old = oldv[ai][m][bj];
;             const float ov[8] = {bflo(old.x), bfhi(old.x), bflo(old.y), bfhi(old.y), bflo(old.z), bfhi(old.z), bflo(old.w), bfhi(old.w)};
; #pragma unroll
;             for (int i = 0; i < 4; ++i) { const float a = v0[i], b = v1[i]; v0[i] = a / (1.f + __expf(-a)) * ov[i]; v1[i] = b / (1.f + __expf(-b)) * ov[4 + i]; }
;           } else if (cs) {
;             const f32x4 s0 = *(const f32x4*)(cs + c), s1 = *(const f32x4*)(cs + c + 4); v0 = v0 * s0; v1 = v1 * s1;
;           }
;           u32x4 w; w.x = cvtpk(v0[0], v0[1]); w.y = cvtpk(v0[2], v0[3]); w.z = cvtpk(v1[0], v1[1]); w.w = cvtpk(v1[2], v1[3]);
;           *(u32x4*)(rowp + c) = w;
	v_pk_mul_f32 v[70:71], v[70:71], v[70:71]
	v_pk_mul_f32 v[72:73], v[66:67], v[66:67]
	v_pk_mul_f32 v[76:77], v[68:69], v[68:69]
	v_cvt_pk_bf16_f32 v66, v70, v71
	v_cvt_pk_bf16_f32 v67, v72, v73
	v_cvt_pk_bf16_f32 v68, v74, v75
	v_cvt_pk_bf16_f32 v69, v76, v77
	v_max_f32_e32 v58, 0, v58
	v_max_f32_e32 v59, 0, v59
	global_store_dwordx4 v[78:79], v[66:69], off offset:256
	s_nop 1
	v_add_u32_e32 v66, 0x80, v140
	v_pk_mul_f32 v[68:69], v[58:59], v[58:59]
	v_ashrrev_i32_e32 v67, 31, v66
	v_max_f32_e32 v60, 0, v60
	v_lshlrev_b64 v[66:67], 13, v[66:67]
	v_max_f32_e32 v62, 0, v62
	v_max_f32_e32 v63, 0, v63
	v_max_f32_e32 v58, 0, v64
	v_max_f32_e32 v59, 0, v65
	v_max_f32_e32 v61, 0, v61
	v_lshl_add_u64 v[66:67], s[84:85], 0, v[66:67]
	v_pk_mul_f32 v[62:63], v[62:63], v[62:63]
	v_pk_mul_f32 v[64:65], v[58:59], v[58:59]
	v_pk_mul_f32 v[70:71], v[60:61], v[60:61]
	v_cvt_pk_bf16_f32 v58, v62, v63
	v_cvt_pk_bf16_f32 v59, v64, v65
	v_cvt_pk_bf16_f32 v60, v68, v69
	v_cvt_pk_bf16_f32 v61, v70, v71
	v_lshl_add_u64 v[62:63], v[66:67], 0, v[122:123]
	v_max_f32_e32 v50, 0, v50
	v_max_f32_e32 v51, 0, v51
	global_store_dwordx4 v[62:63], v[58:61], off
	s_nop 1
	v_pk_mul_f32 v[58:59], v[50:51], v[50:51]
	v_max_f32_e32 v52, 0, v52
	v_max_f32_e32 v54, 0, v54
	v_max_f32_e32 v55, 0, v55
	v_max_f32_e32 v50, 0, v56
	v_max_f32_e32 v51, 0, v57
	v_max_f32_e32 v53, 0, v53
	v_pk_mul_f32 v[54:55], v[54:55], v[54:55]
	v_pk_mul_f32 v[56:57], v[50:51], v[50:51]
	v_pk_mul_f32 v[60:61], v[52:53], v[52:53]
	v_cvt_pk_bf16_f32 v50, v54, v55
	v_cvt_pk_bf16_f32 v51, v56, v57
	v_cvt_pk_bf16_f32 v52, v58, v59
	v_cvt_pk_bf16_f32 v53, v60, v61
	v_max_f32_e32 v42, 0, v42
	v_max_f32_e32 v43, 0, v43
	global_store_dwordx4 v[62:63], v[50:53], off offset:256
	s_nop 1
	v_add_u32_e32 v50, 0x90, v140
	v_pk_mul_f32 v[52:53], v[42:43], v[42:43]
	v_ashrrev_i32_e32 v51, 31, v50
	v_max_f32_e32 v44, 0, v44
	v_lshlrev_b64 v[50:51], 13, v[50:51]
	v_max_f32_e32 v46, 0, v46
	v_max_f32_e32 v47, 0, v47
	v_max_f32_e32 v42, 0, v48
	v_max_f32_e32 v43, 0, v49
	v_max_f32_e32 v45, 0, v45
	v_lshl_add_u64 v[50:51], s[84:85], 0, v[50:51]
	v_pk_mul_f32 v[46:47], v[46:47], v[46:47]
	v_pk_mul_f32 v[48:49], v[42:43], v[42:43]
	v_pk_mul_f32 v[54:55], v[44:45], v[44:45]
	v_cvt_pk_bf16_f32 v42, v46, v47
	v_cvt_pk_bf16_f32 v43, v48, v49
	v_cvt_pk_bf16_f32 v44, v52, v53
	v_cvt_pk_bf16_f32 v45, v54, v55
	v_lshl_add_u64 v[46:47], v[50:51], 0, v[122:123]
	v_max_f32_e32 v34, 0, v34
	v_max_f32_e32 v35, 0, v35
	global_store_dwordx4 v[46:47], v[42:45], off
	s_nop 1
	v_pk_mul_f32 v[42:43], v[34:35], v[34:35]
	v_max_f32_e32 v36, 0, v36
	v_max_f32_e32 v38, 0, v38
	v_max_f32_e32 v39, 0, v39
	v_max_f32_e32 v34, 0, v40
	v_max_f32_e32 v35, 0, v41
	v_max_f32_e32 v37, 0, v37
	v_pk_mul_f32 v[38:39], v[38:39], v[38:39]
	v_pk_mul_f32 v[40:41], v[34:35], v[34:35]
	v_pk_mul_f32 v[44:45], v[36:37], v[36:37]
	v_cvt_pk_bf16_f32 v34, v38, v39
	v_cvt_pk_bf16_f32 v35, v40, v41
	v_cvt_pk_bf16_f32 v36, v42, v43
	v_cvt_pk_bf16_f32 v37, v44, v45
	v_max_f32_e32 v26, 0, v26
	v_max_f32_e32 v27, 0, v27
	global_store_dwordx4 v[46:47], v[34:37], off offset:256
	s_nop 1
	v_add_u32_e32 v34, 0xa0, v140
	v_pk_mul_f32 v[36:37], v[26:27], v[26:27]
	v_ashrrev_i32_e32 v35, 31, v34
	v_max_f32_e32 v28, 0, v28
	v_lshlrev_b64 v[34:35], 13, v[34:35]
	v_max_f32_e32 v30, 0, v30
	v_max_f32_e32 v31, 0, v31
	v_max_f32_e32 v26, 0, v32
	v_max_f32_e32 v27, 0, v33
	v_max_f32_e32 v29, 0, v29
	v_lshl_add_u64 v[34:35], s[84:85], 0, v[34:35]
	v_pk_mul_f32 v[30:31], v[30:31], v[30:31]
	v_pk_mul_f32 v[32:33], v[26:27], v[26:27]
	v_pk_mul_f32 v[38:39], v[28:29], v[28:29]
	v_cvt_pk_bf16_f32 v26, v30, v31
	v_cvt_pk_bf16_f32 v27, v32, v33
	v_cvt_pk_bf16_f32 v28, v36, v37
	v_cvt_pk_bf16_f32 v29, v38, v39
	v_lshl_add_u64 v[30:31], v[34:35], 0, v[122:123]
	v_max_f32_e32 v18, 0, v18
	v_max_f32_e32 v19, 0, v19
	global_store_dwordx4 v[30:31], v[26:29], off
	s_nop 1
	v_pk_mul_f32 v[26:27], v[18:19], v[18:19]
	v_max_f32_e32 v20, 0, v20
	v_max_f32_e32 v22, 0, v22
	v_max_f32_e32 v23, 0, v23
	v_max_f32_e32 v18, 0, v24
	v_max_f32_e32 v19, 0, v25
	v_max_f32_e32 v21, 0, v21
	v_pk_mul_f32 v[22:23], v[22:23], v[22:23]
	v_pk_mul_f32 v[24:25], v[18:19], v[18:19]
	v_pk_mul_f32 v[28:29], v[20:21], v[20:21]
	v_cvt_pk_bf16_f32 v18, v22, v23
	v_cvt_pk_bf16_f32 v19, v24, v25
	v_cvt_pk_bf16_f32 v20, v26, v27
	v_cvt_pk_bf16_f32 v21, v28, v29
	v_max_f32_e32 v10, 0, v10
	v_max_f32_e32 v11, 0, v11
	global_store_dwordx4 v[30:31], v[18:21], off offset:256
	s_nop 1
	v_add_u32_e32 v18, 0xb0, v140
	v_pk_mul_f32 v[20:21], v[10:11], v[10:11]
	v_ashrrev_i32_e32 v19, 31, v18
	v_max_f32_e32 v12, 0, v12
	v_lshlrev_b64 v[18:19], 13, v[18:19]
	v_max_f32_e32 v14, 0, v14
	v_max_f32_e32 v15, 0, v15
	v_max_f32_e32 v10, 0, v16
	v_max_f32_e32 v11, 0, v17
	v_max_f32_e32 v13, 0, v13
	v_lshl_add_u64 v[18:19], s[84:85], 0, v[18:19]
	v_pk_mul_f32 v[14:15], v[14:15], v[14:15]
	v_pk_mul_f32 v[16:17], v[10:11], v[10:11]
	v_pk_mul_f32 v[22:23], v[12:13], v[12:13]
	v_cvt_pk_bf16_f32 v10, v14, v15
	v_cvt_pk_bf16_f32 v11, v16, v17
	v_cvt_pk_bf16_f32 v12, v20, v21
	v_cvt_pk_bf16_f32 v13, v22, v23
	v_lshl_add_u64 v[14:15], v[18:19], 0, v[122:123]
	v_max_f32_e32 v2, 0, v2
	v_max_f32_e32 v3, 0, v3
	global_store_dwordx4 v[14:15], v[10:13], off
	s_nop 1
	v_pk_mul_f32 v[10:11], v[2:3], v[2:3]
	v_max_f32_e32 v4, 0, v4
	v_max_f32_e32 v6, 0, v6
	v_max_f32_e32 v7, 0, v7
	v_max_f32_e32 v2, 0, v8
	v_max_f32_e32 v3, 0, v9
	v_max_f32_e32 v5, 0, v5
	v_pk_mul_f32 v[6:7], v[6:7], v[6:7]
	v_pk_mul_f32 v[8:9], v[2:3], v[2:3]
	v_pk_mul_f32 v[12:13], v[4:5], v[4:5]
	v_cvt_pk_bf16_f32 v2, v6, v7
	v_cvt_pk_bf16_f32 v3, v8, v9
	v_cvt_pk_bf16_f32 v4, v10, v11
	v_cvt_pk_bf16_f32 v5, v12, v13
	s_andn2_b64 vcc, exec, s[4:5]
	s_mov_b64 s[4:5], -1
	global_store_dwordx4 v[14:15], v[2:5], off offset:256
	s_cbranch_vccnz .LBB0_165
	s_andn2_b64 vcc, exec, s[10:11]
	s_cbranch_vccnz .LBB0_164
	s_barrier
	s_branch .LBB0_164

; #define LAS __attribute__((address_space(3)))
; __device__ __forceinline__ void ret_unit(LAS unsigned char* lds, bf16_t* U, bf16_t* OF, int b, int h, int sl, const int tid, const bool dry) {
;   const int lane = tid & 63, wid = tid >> 6, c16 = lane & 15, quad = lane >> 4, tq = (lane & 15) >> 2, tp = lane & 3;
;   LAS bf16_t* Qs = (LAS bf16_t*)(lds + RT_QS); LAS bf16_t* Ks = (LAS bf16_t*)(lds + RT_KS); LAS bf16_t* Vs = (LAS bf16_t*)(lds + RT_VS); LAS bf16_t* St = (LAS bf16_t*)(lds + RT_ST);
;   const size_t rowb = (size_t)b * SEGL;
;   const int n = 16 * wid + c16;
;   for (int dir = 0; dir < 2; ++dir) {
;     const int hh = dir ? (7 - h) : h;
;     const float lg = log2f(1.0f - exp2f(-5.0f - (float)hh));
;     const float gC = exp2f(lg * 128.f), g1 = exp2f(lg), g127 = exp2f(lg * 127.f);
;     const float dq = dir ? exp2f(lg * (float)(128 - n)) : exp2f(lg * (float)(n + 1));
;     const float cn = dir ? exp2f(-lg * (float)n) : exp2f(lg * (float)n);
;     float kf4[4];
; #pragma unroll
;     for (int i = 0; i < 4; ++i) { const int row = (tid + 512 * i) >> 4; kf4[i] = dir ? exp2f(lg * (float)row) : exp2f(-lg * (float)row); }
;     f32x4 st[4];
; #pragma unroll
;     for (int eb = 0; eb < 4; ++eb) st[eb] = (f32x4){0.f, 0.f, 0.f, 0.f};
;     u32x4 rq[4], rk[4], rv[2];
;     { const int c0 = dir ? 1 : 0; const size_t row0 = rowb + (size_t)c0 * 128;
; #pragma unroll
;       for (int i = 0; i < 4; ++i) { const int idx = tid + 512 * i, row = idx >> 4, ch = idx & 15; const bf16_t* src = U + (row0 + row) * 4096 + h * 128 + ch * 8; rq[i] = *(const u32x4*)src; rk[i] = *(const u32x4*)(src + 1024); }
; #pragma unroll
;       for (int i = 0; i < 2; ++i) { const int idx = tid + 512 * i, row = idx >> 3, ch = idx & 7; rv[i] = *(const u32x4*)(U + (row0 + row) * 4096 + 2048 + h * 256 + sl * 64 + ch * 8); } }
;     ...
;             for (int r = 0; r < 4; ++r) { const int m = 16 * mb + 4 * quad + r; const bool keep = dir ? (m > n) : (n >= m); pw[4 * hf + r] = keep ? a[r] * cn : 0.f; } }
.LBB0_239:
	s_and_b64 vcc, exec, s[4:5]
	s_cbranch_vccz .LBB0_275
	s_cmp_gt_i32 s61, 1
	s_mov_b64 s[0:1], -1
	s_cbranch_scc0 .LBB0_273
	v_writelane_b32 v253, s82, 39
	s_nop 1
	v_writelane_b32 v253, s83, 40
	v_writelane_b32 v253, s80, 41
	s_nop 1
	v_writelane_b32 v253, s81, 42
	v_writelane_b32 v253, s71, 43
	v_writelane_b32 v253, s78, 44
	s_nop 1
	v_writelane_b32 v253, s79, 45
	v_writelane_b32 v253, s76, 46
	s_nop 1
	v_writelane_b32 v253, s77, 47
	v_writelane_b32 v253, s74, 48
	s_nop 1
	v_writelane_b32 v253, s75, 49
	v_writelane_b32 v253, s72, 50
	s_nop 1
	v_writelane_b32 v253, s73, 51
	v_writelane_b32 v253, s68, 52
	s_nop 1
	v_writelane_b32 v253, s69, 53
	v_writelane_b32 v253, s2, 54
	s_nop 0
	v_readlane_b32 s0, v253, 23
	s_cmpk_gt_i32 s0, 0xff
	s_cbranch_scc1 .LBB0_272
	v_lshlrev_b32_e32 v0, 4, v194
	s_waitcnt vmcnt(7)
	v_add_u32_e32 v15, 0x400, v194
	v_ashrrev_i32_e32 v2, 6, v194
	v_and_b32_e32 v3, 15, v194
	v_bfe_u32 v4, v194, 4, 2
	v_lshlrev_b32_e32 v6, 3, v194
	v_and_b32_e32 v0, 0xf0, v0
	v_add_u32_e32 v14, 0x200, v194
	v_ashrrev_i32_e32 v118, 4, v15
	v_add_u32_e32 v15, 0x600, v194
	v_lshl_add_u64 v[108:109], s[84:85], 0, v[0:1]
	v_and_b32_e32 v110, 56, v6
	v_add_u32_e32 v0, 0, v0
	v_readlane_b32 s0, v253, 10
	v_lshlrev_b32_e32 v8, 5, v2
	v_lshlrev_b32_e32 v9, 1, v3
	v_readlane_b32 s1, v253, 11
	s_movk_i32 s2, 0x110
	v_lshlrev_b32_e32 v11, 4, v4
	v_and_b32_e32 v6, 24, v6
	v_ashrrev_i32_e32 v114, 4, v194
	v_ashrrev_i32_e32 v116, 4, v14
	v_ashrrev_i32_e32 v120, 4, v15
	v_lshl_add_u32 v7, v110, 1, s0
	v_add3_u32 v9, s1, v8, v9
	v_add_u32_e32 v12, s1, v11
	v_add_u32_e32 v13, s0, v6
	v_mad_u64_u32 v[126:127], s[0:1], v114, s2, v[0:1]
	v_mad_u64_u32 v[128:129], s[0:1], v116, s2, v[0:1]
	v_mad_u64_u32 v[130:131], s[0:1], v118, s2, v[0:1]
	v_mad_u64_u32 v[132:133], s[0:1], v120, s2, v[0:1]
	v_ashrrev_i32_e32 v122, 3, v194
	v_ashrrev_i32_e32 v124, 3, v14
	s_movk_i32 s0, 0x90
	v_mul_lo_u32 v0, v122, s0
	v_mul_lo_u32 v14, v124, s0
	v_cmp_gt_i32_e64 s[0:1], 2, v2
	v_lshl_or_b32 v106, v2, 4, v3
	v_lshlrev_b32_e32 v112, 2, v4
	v_writelane_b32 v253, s0, 55
	v_or_b32_e32 v15, 2, v112
	v_or_b32_e32 v17, 3, v112
	v_writelane_b32 v253, s1, 56
	v_cmp_lt_i32_e64 s[0:1], -1, v2
	s_waitcnt vmcnt(6)
	v_or_b32_e32 v18, 16, v112
	v_or_b32_e32 v19, 17, v112
	v_writelane_b32 v253, s0, 57
	v_or_b32_e32 v20, 18, v112
	v_or_b32_e32 v21, 19, v112
	v_writelane_b32 v253, s1, 58
	v_cmp_gt_i32_e64 s[0:1], v112, v106
	s_waitcnt vmcnt(5)
	v_or_b32_e32 v22, 32, v112
	v_or_b32_e32 v23, 33, v112
	v_writelane_b32 v253, s0, 59
	v_or_b32_e32 v24, 34, v112
	v_or_b32_e32 v25, 35, v112
	v_writelane_b32 v253, s1, 60
	v_cmp_ge_i32_e64 s[0:1], v112, v106
	s_waitcnt vmcnt(4)
	v_or_b32_e32 v26, 48, v112
	v_or_b32_e32 v27, 49, v112
	v_writelane_b32 v253, s0, 61
	v_or_b32_e32 v28, 50, v112
	v_or_b32_e32 v29, 51, v112
	v_writelane_b32 v253, s1, 62
	v_cmp_gt_i32_e64 s[0:1], v15, v106
	v_mul_u32_u24_e32 v16, 0x110, v15
	v_or_b32_e32 v15, 64, v112
	v_writelane_b32 v253, s0, 63
	v_bfe_u32 v5, v194, 2, 2
	v_cvt_f32_i32_e32 v195, v106
	v_writelane_b32 v254, s1, 0
	v_cmp_gt_i32_e64 s[0:1], v17, v106
	v_cvt_f32_i32_e32 v198, v114
	v_cvt_f32_i32_e32 v199, v116
	v_writelane_b32 v254, s0, 1
	v_cvt_f32_i32_e32 v200, v118
	v_cvt_f32_i32_e32 v201, v120
	v_writelane_b32 v254, s1, 2
	v_cmp_gt_i32_e64 s[0:1], v18, v106
	v_mul_lo_u32 v10, v106, s2
	v_or_b32_e32 v5, v112, v5
	v_writelane_b32 v254, s0, 3
	v_add_u32_e32 v10, 0, v10
	v_add3_u32 v6, 0, v8, v6
	v_writelane_b32 v254, s1, 4
	v_cmp_gt_i32_e64 s[0:1], v19, v106
	v_add_u32_e32 v8, 0, v11
	v_mul_u32_u24_e32 v4, 0x440, v4
	v_writelane_b32 v254, s0, 5
	v_mul_u32_u24_e32 v3, 0x110, v3
	s_waitcnt vmcnt(3)
; __device__ __forceinline__ void ret_unit(LAS unsigned char* lds, bf16_t* U, bf16_t* OF, int b, int h, int sl, const int tid, const bool dry) {
;     ...
;       for (int i = 0; i < 4; ++i) { const int idx = tid + 512 * i, row = idx >> 4, ch = idx & 15;
;         *(LAS u32x4*)(Qs + row * RT_STR + ch * 8) = rq[i]; *(LAS u32x4*)(Ks + row * RT_STR + ch * 8) = scale8(rk[i], kf4[i]); }
; #pragma unroll
;       for (int i = 0; i < 2; ++i) { const int idx = tid + 512 * i, row = idx >> 3, ch = idx & 7; *(LAS u32x4*)(Vs + row * RT_VSTR + ch * 8) = rv[i]; }
; #pragma unroll
;       for (int eb = 0; eb < 4; ++eb)
; #pragma unroll
;         for (int r = 0; r < 4; ++r) St[(16 * eb + 4 * quad + r) * RT_STR + 16 * wid + c16] = f2bf(st[eb][r]);
;       __syncthreads();
;       if (step + 1 < 66) { const int s1 = step + 1; const int c1 = dir ? ((s1 < 2) ? (1 - s1) : (67 - s1)) : s1; const size_t r1 = rowb + (size_t)c1 * 128;
; #pragma unroll
;         for (int i = 0; i < 4; ++i) { const int idx = tid + 512 * i, row = idx >> 4, ch = idx & 15; const bf16_t* src = U + (r1 + row) * 4096 + h * 128 + ch * 8; rq[i] = *(const u32x4*)src; rk[i] = *(const u32x4*)(src + 1024); }
; #pragma unroll
;         for (int i = 0; i < 2; ++i) { const int idx = tid + 512 * i, row = idx >> 3, ch = idx & 7; rv[i] = *(const u32x4*)(U + (r1 + row) * 4096 + 2048 + h * 256 + sl * 64 + ch * 8); } }
;       u32x2 fo[4];
;       if (dir) { const bf16_t* ip = OF + grow * 2048 + h * 256 + sl * 64 + quad * 4;
; #pragma unroll
;         for (int eb = 0; eb < 4; ++eb) fo[eb] = *(const u32x2*)(ip + eb * 16); }
;       bf16x8 qf[4];
; #pragma unroll
;       for (int ks = 0; ks < 4; ++ks) qf[ks] = *(const LAS bf16x8*)(Qs + n * RT_STR + ks * 32 + quad * 8);
;       f32x4 o[4];
; #pragma unroll
;       for (int eb = 0; eb < 4; ++eb) { f32x4 a = (f32x4){0.f, 0.f, 0.f, 0.f};
; #pragma unroll
;         for (int ks = 0; ks < 4; ++ks) { const bf16x8 af = *(const LAS bf16x8*)(St + (16 * eb + c16) * RT_STR + ks * 32 + quad * 8); a = mfma16(af, qf[ks], a); }
;         o[eb] = a * dq; }
;       const float pre = dir ? gC : g1, post = dir ? 1.f : g127;
; #pragma unroll
;       for (int eb = 0; eb < 4; ++eb) st[eb] = st[eb] * pre;
; #pragma unroll 4
;       for (int s2 = 0; s2 < 4; ++s2) {
;         const LAS bf16_t* vb = Vs + (32 * s2 + 4 * quad + tq) * RT_VSTR + 4 * tp;
;         bf16x8 vf[4];
; #pragma unroll
	v_mul_u32_u24_e32 v30, 0x90, v5
	v_writelane_b32 v254, s1, 6
	v_cmp_gt_i32_e64 s[0:1], v20, v106
	v_mul_u32_u24_e32 v5, 0x110, v5
	v_ashrrev_i32_e32 v107, 31, v106
	v_writelane_b32 v254, s0, 7
	v_sub_u32_e32 v111, 0x80, v106
	v_add_u32_e32 v113, 1, v106
	v_writelane_b32 v254, s1, 8
	v_cmp_gt_i32_e64 s[0:1], v21, v106
	v_ashrrev_i32_e32 v115, 31, v114
	v_ashrrev_i32_e32 v117, 31, v116
	v_writelane_b32 v254, s0, 9
	v_ashrrev_i32_e32 v119, 31, v118
	v_ashrrev_i32_e32 v121, 31, v120
	v_writelane_b32 v254, s1, 10
	v_cmp_gt_i32_e64 s[0:1], 4, v2
	v_ashrrev_i32_e32 v123, 31, v122
	v_ashrrev_i32_e32 v125, 31, v124
	v_writelane_b32 v254, s0, 11
	v_add_u32_e32 v127, v7, v0
	v_add_u32_e32 v129, v7, v14
	v_writelane_b32 v254, s1, 12
	v_cmp_lt_i32_e64 s[0:1], 1, v2
	v_add_u32_e32 v131, v9, v4
	v_add_u32_e32 v133, v9, v16
	v_writelane_b32 v254, s0, 13
	v_add_u32_e32 v202, v10, v11
	v_add_u32_e32 v203, v12, v3
	v_writelane_b32 v254, s1, 14
	v_cmp_gt_i32_e64 s[0:1], v22, v106
	v_add_u32_e32 v204, v13, v30
	v_bfe_u32 v212, v194, 3, 1
	v_lshlrev_b32_e32 v212, 4, v212
	v_sub_u32_e32 v127, v127, v212
	v_sub_u32_e32 v129, v129, v212
	v_bfe_u32 v212, v194, 2, 1
	v_lshlrev_b32_e32 v212, 4, v212
	v_sub_u32_e32 v204, v204, v212
	v_add_u32_e32 v205, v8, v3
	v_writelane_b32 v254, s0, 15
	v_add_u32_e32 v206, v6, v5
	v_readlane_b32 s2, v253, 23
	v_writelane_b32 v254, s1, 16
	v_cmp_gt_i32_e64 s[0:1], v23, v106
	s_nop 1
	v_writelane_b32 v254, s0, 17
	s_nop 1
	v_writelane_b32 v254, s1, 18
	v_cmp_gt_i32_e64 s[0:1], v24, v106
	s_nop 1
	v_writelane_b32 v254, s0, 19
	s_nop 1
	v_writelane_b32 v254, s1, 20
	v_cmp_gt_i32_e64 s[0:1], v25, v106
	s_nop 1
	v_writelane_b32 v254, s0, 21
	s_nop 1
	v_writelane_b32 v254, s1, 22
	v_cmp_gt_i32_e64 s[0:1], v26, v106
	s_nop 1
	v_writelane_b32 v254, s0, 23
	s_nop 1
	v_writelane_b32 v254, s1, 24
	v_cmp_gt_i32_e64 s[0:1], v27, v106
	s_nop 1
	v_writelane_b32 v254, s0, 25
	s_nop 1
	v_writelane_b32 v254, s1, 26
	v_cmp_gt_i32_e64 s[0:1], v28, v106
	s_nop 1
	v_writelane_b32 v254, s0, 27
	s_nop 1
	v_writelane_b32 v254, s1, 28
	v_cmp_gt_i32_e64 s[0:1], v29, v106
	s_nop 1
	v_writelane_b32 v254, s0, 29
	s_nop 1
	v_writelane_b32 v254, s1, 30
	v_cmp_gt_i32_e64 s[0:1], 6, v2
	s_nop 1
	v_writelane_b32 v254, s0, 31
	s_nop 1
	v_writelane_b32 v254, s1, 32
	v_cmp_lt_i32_e64 s[0:1], 3, v2
	s_nop 1
	v_writelane_b32 v254, s0, 33
	s_nop 1
	v_writelane_b32 v254, s1, 34
	v_cmp_gt_i32_e64 s[0:1], v15, v106
	v_or_b32_e32 v15, 0x41, v112
	s_nop 0
	v_writelane_b32 v254, s0, 35
	s_nop 1
	v_writelane_b32 v254, s1, 36
	v_cmp_gt_i32_e64 s[0:1], v15, v106
	v_or_b32_e32 v15, 0x42, v112
	s_nop 0
	v_writelane_b32 v254, s0, 37
	s_nop 1
	v_writelane_b32 v254, s1, 38
	v_cmp_gt_i32_e64 s[0:1], v15, v106
	v_or_b32_e32 v15, 0x43, v112
	s_nop 0
	v_writelane_b32 v254, s0, 39
	s_nop 1
	v_writelane_b32 v254, s1, 40
	v_cmp_gt_i32_e64 s[0:1], v15, v106
	v_or_b32_e32 v15, 0x50, v112
	s_nop 0
	v_writelane_b32 v254, s0, 41
	s_nop 1
	v_writelane_b32 v254, s1, 42
	v_cmp_gt_i32_e64 s[0:1], v15, v106
	v_or_b32_e32 v15, 0x51, v112
	s_nop 0
	v_writelane_b32 v254, s0, 43
	s_nop 1
	v_writelane_b32 v254, s1, 44
	v_cmp_gt_i32_e64 s[0:1], v15, v106
	v_or_b32_e32 v15, 0x52, v112
	s_nop 0
	v_writelane_b32 v254, s0, 45
	s_nop 1
	v_writelane_b32 v254, s1, 46
	v_cmp_gt_i32_e64 s[0:1], v15, v106
	v_or_b32_e32 v15, 0x53, v112
	s_nop 0
	v_writelane_b32 v254, s0, 47
	s_nop 1
	v_writelane_b32 v254, s1, 48
	v_cmp_gt_i32_e64 s[0:1], v15, v106
	s_nop 1
	v_writelane_b32 v254, s0, 49
	s_nop 1
	v_writelane_b32 v254, s1, 50
	v_cmp_gt_i32_e64 s[0:1], 8, v2
	s_nop 1
	v_writelane_b32 v254, s0, 51
	s_nop 1
	v_writelane_b32 v254, s1, 52
	v_cmp_lt_i32_e64 s[0:1], 5, v2
	v_or_b32_e32 v2, 0x60, v112
	s_nop 0
	v_writelane_b32 v254, s0, 53
	s_nop 1
	v_writelane_b32 v254, s1, 54
	v_cmp_gt_i32_e64 s[0:1], v2, v106
	v_or_b32_e32 v2, 0x61, v112
	s_nop 0
	v_writelane_b32 v254, s0, 55
	s_nop 1
	v_writelane_b32 v254, s1, 56
	v_cmp_gt_i32_e64 s[0:1], v2, v106
	v_or_b32_e32 v2, 0x62, v112
	s_nop 0
	v_writelane_b32 v254, s0, 57
	s_nop 1
	v_writelane_b32 v254, s1, 58
	v_cmp_gt_i32_e64 s[0:1], v2, v106
	v_or_b32_e32 v2, 0x63, v112
	s_nop 0
	v_writelane_b32 v254, s0, 59
	s_nop 1
	v_writelane_b32 v254, s1, 60
	v_cmp_gt_i32_e64 s[0:1], v2, v106
	v_or_b32_e32 v2, 0x70, v112
	s_nop 0
	v_writelane_b32 v254, s0, 61
	s_nop 1
	v_writelane_b32 v254, s1, 62
	v_cmp_gt_i32_e64 s[0:1], v2, v106
	v_or_b32_e32 v2, 0x71, v112
	s_nop 0
	v_writelane_b32 v254, s0, 63
	s_nop 1
	v_writelane_b32 v250, s1, 0
	v_cmp_gt_i32_e64 s[0:1], v2, v106
	v_or_b32_e32 v2, 0x72, v112
	s_nop 0
	v_writelane_b32 v250, s0, 1
	s_nop 1
	v_writelane_b32 v250, s1, 2
	v_cmp_gt_i32_e64 s[0:1], v2, v106
	v_or_b32_e32 v2, 0x73, v112
	s_nop 0
	v_writelane_b32 v250, s0, 3
	s_nop 1
	v_writelane_b32 v250, s1, 4
	v_cmp_gt_i32_e64 s[0:1], v2, v106
	s_nop 1
	v_writelane_b32 v250, s0, 5
	s_nop 1
	v_writelane_b32 v250, s1, 6
	v_writelane_b32 v250, s70, 7
	v_writelane_b32 v250, s92, 8
	s_nop 1
	v_writelane_b32 v250, s93, 9
	v_writelane_b32 v250, s94, 10
	s_nop 1
	v_writelane_b32 v250, s95, 11
	s_branch .LBB0_244
